# phase_tail gate: rank-16 dot products via f32-operand MFMA (v_mfma_f32_16x16x4_f32) instead of broadcast LDS reads + packed f32 FMAs; f16x4 8-byte stores; same f32 logsigmoid
# speedup vs baseline: 1.0195x; 1.0052x over previous
.LBB0_225:
	v_lshrrev_b32_e32 v98, 8, v0
	v_bfe_u32 v99, v0, 4, 2
	v_lshl_add_u32 v98, v98, 4, v99
	v_lshlrev_b32_e32 v98, 10, v98
	v_bfe_u32 v99, v0, 6, 2
	v_lshlrev_b32_e32 v99, 8, v99
	v_and_b32_e32 v116, 15, v0
	v_lshl_add_u32 v99, v116, 4, v99
	v_add_u32_e32 v98, v98, v99
	s_add_u32 s4, s60, 0x1000
	s_addc_u32 s5, s61, 0
	s_add_u32 s6, s60, 0x2000
	s_addc_u32 s7, s61, 0
	s_add_u32 s8, s60, 0x3000
	s_addc_u32 s9, s61, 0
	global_load_dwordx4 v[100:103], v98, s[60:61]
	global_load_dwordx4 v[104:107], v98, s[4:5]
	global_load_dwordx4 v[108:111], v98, s[6:7]
	global_load_dwordx4 v[112:115], v98, s[8:9]
	v_lshrrev_b32_e32 v99, 6, v0
	v_lshlrev_b32_e32 v99, 8, v99
	v_lshl_add_u32 v99, v116, 4, v99
	global_load_dwordx4 v[116:119], v99, s[62:63]
	s_mul_i32 s4, s19, 48
	v_or_b32_e32 v40, s4, v34
	v_ashrrev_i32_e32 v41, 31, v40
	v_lshlrev_b64 v[40:41], 11, v[40:41]
	v_lshl_add_u64 v[88:89], v[18:19], 0, v[40:41]
	v_add_co_u32_e32 v90, vcc, 0x8000, v88
	global_load_dwordx4 v[40:43], v[88:89], off
	global_load_dwordx4 v[44:47], v[20:21], off
	global_load_dwordx4 v[48:51], v[22:23], off
	v_addc_co_u32_e32 v91, vcc, 0, v89, vcc
	v_add_co_u32_e32 v96, vcc, 0x10000, v88
	global_load_dwordx4 v[52:55], v[90:91], off
	global_load_dwordx4 v[56:59], v[20:21], off offset:64
	global_load_dwordx4 v[60:63], v[88:89], off offset:64
	v_addc_co_u32_e32 v97, vcc, 0, v89, vcc
	global_load_dwordx4 v[80:83], v[96:97], off
	global_load_dwordx4 v[84:87], v[96:97], off offset:64
	global_load_dwordx4 v[68:71], v[26:27], off
	global_load_dwordx4 v[72:75], v[90:91], off offset:64
	s_waitcnt vmcnt(8)
	v_mfma_f32_16x16x32_bf16 v[64:67], v[40:43], v[44:47], 0
	s_waitcnt vmcnt(7)
	v_mfma_f32_16x16x32_bf16 v[40:43], v[40:43], v[48:51], 0
	s_waitcnt vmcnt(6)
	v_mfma_f32_16x16x32_bf16 v[76:79], v[52:55], v[44:47], 0
	s_waitcnt vmcnt(3)
	v_mfma_f32_16x16x32_bf16 v[44:47], v[80:83], v[44:47], 0
	v_mfma_f32_16x16x32_bf16 v[64:67], v[60:63], v[56:59], v[64:67]
	s_waitcnt vmcnt(1)
	v_mfma_f32_16x16x32_bf16 v[40:43], v[60:63], v[68:71], v[40:43]
	s_waitcnt vmcnt(0)
	v_mfma_f32_16x16x32_bf16 v[60:63], v[72:75], v[56:59], v[76:79]
	v_mfma_f32_16x16x32_bf16 v[44:47], v[84:87], v[56:59], v[44:47]
	global_load_dwordx4 v[56:59], v[88:89], off offset:128
	v_mfma_f32_16x16x32_bf16 v[52:55], v[52:55], v[48:51], 0
	v_mfma_f32_16x16x32_bf16 v[48:51], v[80:83], v[48:51], 0
	v_mfma_f32_16x16x32_bf16 v[52:55], v[72:75], v[68:71], v[52:55]
	v_mfma_f32_16x16x32_bf16 v[48:51], v[84:87], v[68:71], v[48:51]
	global_load_dwordx4 v[68:71], v[20:21], off offset:128
	global_load_dwordx4 v[72:75], v[20:21], off offset:192
	global_load_dwordx4 v[76:79], v[88:89], off offset:192
	global_load_dwordx4 v[80:83], v[28:29], off
	global_load_dwordx4 v[84:87], v[30:31], off
	s_waitcnt vmcnt(4)
	v_mfma_f32_16x16x32_bf16 v[64:67], v[56:59], v[68:71], v[64:67]
	s_waitcnt vmcnt(1)
	v_mfma_f32_16x16x32_bf16 v[40:43], v[56:59], v[80:83], v[40:43]
	global_load_dwordx4 v[56:59], v[90:91], off offset:128
	s_nop 0
	global_load_dwordx4 v[88:91], v[90:91], off offset:192
	s_nop 0
	global_load_dwordx4 v[92:95], v[96:97], off offset:128
	v_mfma_f32_16x16x32_bf16 v[64:67], v[76:79], v[72:75], v[64:67]
	s_waitcnt vmcnt(3)
	v_mfma_f32_16x16x32_bf16 v[40:43], v[76:79], v[84:87], v[40:43]
	s_waitcnt vmcnt(2)
	v_mfma_f32_16x16x32_bf16 v[60:63], v[56:59], v[68:71], v[60:63]
	v_mfma_f32_16x16x32_bf16 v[52:55], v[56:59], v[80:83], v[52:55]
	global_load_dwordx4 v[56:59], v[96:97], off offset:192
	s_waitcnt vmcnt(1)
	v_mfma_f32_16x16x32_bf16 v[44:47], v[92:95], v[68:71], v[44:47]
	v_add_u32_e32 v68, v35, v1
	v_mfma_f32_16x16x32_bf16 v[48:51], v[92:95], v[80:83], v[48:51]
	v_mfma_f32_16x16x32_bf16 v[60:63], v[88:91], v[72:75], v[60:63]
	v_mfma_f32_16x16x32_bf16 v[52:55], v[88:91], v[84:87], v[52:55]
	s_waitcnt vmcnt(0)
	v_mfma_f32_16x16x32_bf16 v[44:47], v[56:59], v[72:75], v[44:47]
	v_mfma_f32_16x16x32_bf16 v[48:51], v[56:59], v[84:87], v[48:51]
	ds_write2_b32 v68, v64, v40 offset1:16
	ds_write2_b32 v68, v65, v41 offset0:33 offset1:49
	ds_write2_b32 v68, v66, v42 offset0:66 offset1:82
	ds_write2_b32 v68, v67, v43 offset0:99 offset1:115
	s_nop 0
	ds_write2_b32 v37, v60, v52 offset1:16
	ds_write2_b32 v37, v61, v53 offset0:33 offset1:49
	ds_write2_b32 v37, v62, v54 offset0:66 offset1:82
	ds_write2_b32 v37, v63, v55 offset0:99 offset1:115
	ds_write2_b32 v38, v44, v48 offset1:16
	ds_write2_b32 v38, v45, v49 offset0:33 offset1:49
	ds_write2_b32 v38, v46, v50 offset0:66 offset1:82
	ds_write2_b32 v38, v47, v51 offset0:99 offset1:115
	s_waitcnt lgkmcnt(0)
	s_barrier
	s_and_saveexec_b64 s[4:5], s[0:1]
	s_cbranch_execz .LBB0_228
	s_mov_b64 s[6:7], 0
	v_mov_b32_e32 v40, v0

.Ltail_gate:
	v_and_b32_e32 v53, 15, v0
	v_bfe_u32 v54, v0, 4, 2
	v_lshrrev_b32_e32 v55, 8, v0
	v_mul_u32_u24_e32 v40, 0x90, v53
	v_lshl_add_u32 v40, v54, 2, v40
	v_lshl_add_u32 v40, v55, 6, v40
	v_add_u32_e32 v40, 0xc600, v40
	ds_read_b32 v41, v40
	ds_read_b32 v42, v40 offset:16
	ds_read_b32 v43, v40 offset:32
	ds_read_b32 v44, v40 offset:48
	ds_read_b32 v45, v40 offset:2304
	ds_read_b32 v46, v40 offset:2320
	ds_read_b32 v47, v40 offset:2336
	ds_read_b32 v48, v40 offset:2352
	ds_read_b32 v49, v40 offset:4608
	ds_read_b32 v50, v40 offset:4624
	ds_read_b32 v51, v40 offset:4640
	ds_read_b32 v52, v40 offset:4656
	s_ashr_i32 s5, s10, 31
	s_mov_b32 s4, s10
	s_lshl_b64 s[4:5], s[4:5], 10
	s_add_u32 s4, s4, s24
	s_addc_u32 s5, s5, s25
	s_add_u32 s4, s4, 0x7522000
	s_addc_u32 s5, s5, 0
	v_lshrrev_b32_e32 v55, 6, v0
	v_lshlrev_b32_e32 v56, 12, v54
	v_lshl_add_u32 v56, v55, 7, v56
	v_lshl_add_u32 v56, v53, 3, v56
	v_mov_b32_e32 v57, 0
	v_lshl_add_u64 v[168:169], s[4:5], 0, v[56:57]
	s_mov_b64 s[6:7], 0x4000
	v_lshl_add_u64 v[170:171], v[168:169], 0, s[6:7]
	v_lshl_add_u64 v[172:173], v[170:171], 0, s[6:7]
	s_waitcnt vmcnt(0) lgkmcnt(0)
	v_mfma_f32_16x16x4_f32 v[120:123], v41, v100, 0
	v_mfma_f32_16x16x4_f32 v[124:127], v41, v101, 0
	v_mfma_f32_16x16x4_f32 v[128:131], v41, v102, 0
	v_mfma_f32_16x16x4_f32 v[132:135], v41, v103, 0
	v_mfma_f32_16x16x4_f32 v[136:139], v45, v100, 0
	v_mfma_f32_16x16x4_f32 v[140:143], v45, v101, 0
	v_mfma_f32_16x16x4_f32 v[144:147], v45, v102, 0
	v_mfma_f32_16x16x4_f32 v[148:151], v45, v103, 0
	v_mfma_f32_16x16x4_f32 v[152:155], v49, v100, 0
	v_mfma_f32_16x16x4_f32 v[156:159], v49, v101, 0
	v_mfma_f32_16x16x4_f32 v[160:163], v49, v102, 0
	v_mfma_f32_16x16x4_f32 v[164:167], v49, v103, 0
	v_mfma_f32_16x16x4_f32 v[120:123], v42, v104, v[120:123]
	v_mfma_f32_16x16x4_f32 v[124:127], v42, v105, v[124:127]
	v_mfma_f32_16x16x4_f32 v[128:131], v42, v106, v[128:131]
	v_mfma_f32_16x16x4_f32 v[132:135], v42, v107, v[132:135]
	v_mfma_f32_16x16x4_f32 v[136:139], v46, v104, v[136:139]
	v_mfma_f32_16x16x4_f32 v[140:143], v46, v105, v[140:143]
	v_mfma_f32_16x16x4_f32 v[144:147], v46, v106, v[144:147]
	v_mfma_f32_16x16x4_f32 v[148:151], v46, v107, v[148:151]
	v_mfma_f32_16x16x4_f32 v[152:155], v50, v104, v[152:155]
	v_mfma_f32_16x16x4_f32 v[156:159], v50, v105, v[156:159]
	v_mfma_f32_16x16x4_f32 v[160:163], v50, v106, v[160:163]
	v_mfma_f32_16x16x4_f32 v[164:167], v50, v107, v[164:167]
	v_mfma_f32_16x16x4_f32 v[120:123], v43, v108, v[120:123]
	v_mfma_f32_16x16x4_f32 v[124:127], v43, v109, v[124:127]
	v_mfma_f32_16x16x4_f32 v[128:131], v43, v110, v[128:131]
	v_mfma_f32_16x16x4_f32 v[132:135], v43, v111, v[132:135]
	v_mfma_f32_16x16x4_f32 v[136:139], v47, v108, v[136:139]
	v_mfma_f32_16x16x4_f32 v[140:143], v47, v109, v[140:143]
	v_mfma_f32_16x16x4_f32 v[144:147], v47, v110, v[144:147]
	v_mfma_f32_16x16x4_f32 v[148:151], v47, v111, v[148:151]
	v_mfma_f32_16x16x4_f32 v[152:155], v51, v108, v[152:155]
	v_mfma_f32_16x16x4_f32 v[156:159], v51, v109, v[156:159]
	v_mfma_f32_16x16x4_f32 v[160:163], v51, v110, v[160:163]
	v_mfma_f32_16x16x4_f32 v[164:167], v51, v111, v[164:167]
	v_mfma_f32_16x16x4_f32 v[120:123], v44, v112, v[120:123]
	v_mfma_f32_16x16x4_f32 v[124:127], v44, v113, v[124:127]
	v_mfma_f32_16x16x4_f32 v[128:131], v44, v114, v[128:131]
	v_mfma_f32_16x16x4_f32 v[132:135], v44, v115, v[132:135]
	v_mfma_f32_16x16x4_f32 v[136:139], v48, v112, v[136:139]
	v_mfma_f32_16x16x4_f32 v[140:143], v48, v113, v[140:143]
	v_mfma_f32_16x16x4_f32 v[144:147], v48, v114, v[144:147]
	v_mfma_f32_16x16x4_f32 v[148:151], v48, v115, v[148:151]
	v_mfma_f32_16x16x4_f32 v[152:155], v52, v112, v[152:155]
	v_mfma_f32_16x16x4_f32 v[156:159], v52, v113, v[156:159]
	v_mfma_f32_16x16x4_f32 v[160:163], v52, v114, v[160:163]
	v_mfma_f32_16x16x4_f32 v[164:167], v52, v115, v[164:167]
	s_nop 7
	s_nop 7
	s_nop 3
	v_add_f32_e32 v120, v116, v120
	v_add_f32_e32 v124, v117, v124
	v_add_f32_e32 v128, v118, v128
	v_add_f32_e32 v132, v119, v132
	v_add_f32_e32 v121, v116, v121
	v_add_f32_e32 v125, v117, v125
	v_add_f32_e32 v129, v118, v129
	v_add_f32_e32 v133, v119, v133
	v_add_f32_e32 v122, v116, v122
	v_add_f32_e32 v126, v117, v126
	v_add_f32_e32 v130, v118, v130
	v_add_f32_e32 v134, v119, v134
	v_add_f32_e32 v123, v116, v123
	v_add_f32_e32 v127, v117, v127
	v_add_f32_e32 v131, v118, v131
	v_add_f32_e32 v135, v119, v135
	v_min_f32_e32 v53, 0, v120
	v_min_f32_e32 v54, 0, v124
	v_min_f32_e32 v55, 0, v128
	v_min_f32_e32 v56, 0, v132
	v_min_f32_e32 v57, 0, v121
	v_min_f32_e32 v58, 0, v125
	v_min_f32_e32 v59, 0, v129
	v_min_f32_e32 v60, 0, v133
	v_min_f32_e32 v61, 0, v122
	v_min_f32_e32 v62, 0, v126
	v_min_f32_e32 v63, 0, v130
	v_min_f32_e32 v64, 0, v134
	v_min_f32_e32 v65, 0, v123
	v_min_f32_e32 v66, 0, v127
	v_min_f32_e32 v67, 0, v131
	v_min_f32_e32 v68, 0, v135
	v_mul_f32_e64 v120, |v120|, s13
	v_mul_f32_e64 v124, |v124|, s13
	v_mul_f32_e64 v128, |v128|, s13
	v_mul_f32_e64 v132, |v132|, s13
	v_mul_f32_e64 v121, |v121|, s13
	v_mul_f32_e64 v125, |v125|, s13
	v_mul_f32_e64 v129, |v129|, s13
	v_mul_f32_e64 v133, |v133|, s13
	v_mul_f32_e64 v122, |v122|, s13
	v_mul_f32_e64 v126, |v126|, s13
	v_mul_f32_e64 v130, |v130|, s13
	v_mul_f32_e64 v134, |v134|, s13
	v_mul_f32_e64 v123, |v123|, s13
	v_mul_f32_e64 v127, |v127|, s13
	v_mul_f32_e64 v131, |v131|, s13
	v_mul_f32_e64 v135, |v135|, s13
	v_exp_f32_e32 v120, v120
	v_exp_f32_e32 v124, v124
	v_exp_f32_e32 v128, v128
	v_exp_f32_e32 v132, v132
	v_exp_f32_e32 v121, v121
	v_exp_f32_e32 v125, v125
	v_exp_f32_e32 v129, v129
	v_exp_f32_e32 v133, v133
	v_exp_f32_e32 v122, v122
	v_exp_f32_e32 v126, v126
	v_exp_f32_e32 v130, v130
	v_exp_f32_e32 v134, v134
	v_exp_f32_e32 v123, v123
	v_exp_f32_e32 v127, v127
	v_exp_f32_e32 v131, v131
	v_exp_f32_e32 v135, v135
	v_add_f32_e32 v120, 1.0, v120
	v_add_f32_e32 v124, 1.0, v124
	v_add_f32_e32 v128, 1.0, v128
	v_add_f32_e32 v132, 1.0, v132
	v_add_f32_e32 v121, 1.0, v121
	v_add_f32_e32 v125, 1.0, v125
	v_add_f32_e32 v129, 1.0, v129
	v_add_f32_e32 v133, 1.0, v133
	v_add_f32_e32 v122, 1.0, v122
	v_add_f32_e32 v126, 1.0, v126
	v_add_f32_e32 v130, 1.0, v130
	v_add_f32_e32 v134, 1.0, v134
	v_add_f32_e32 v123, 1.0, v123
	v_add_f32_e32 v127, 1.0, v127
	v_add_f32_e32 v131, 1.0, v131
	v_add_f32_e32 v135, 1.0, v135
	v_log_f32_e32 v120, v120
	v_log_f32_e32 v124, v124
	v_log_f32_e32 v128, v128
	v_log_f32_e32 v132, v132
	v_log_f32_e32 v121, v121
	v_log_f32_e32 v125, v125
	v_log_f32_e32 v129, v129
	v_log_f32_e32 v133, v133
	v_log_f32_e32 v122, v122
	v_log_f32_e32 v126, v126
	v_log_f32_e32 v130, v130
	v_log_f32_e32 v134, v134
	v_log_f32_e32 v123, v123
	v_log_f32_e32 v127, v127
	v_log_f32_e32 v131, v131
	v_log_f32_e32 v135, v135
	v_mul_f32_e32 v69, 0x3f317217, v120
	v_mul_f32_e32 v70, 0x3f317217, v124
	v_mul_f32_e32 v71, 0x3f317217, v128
	v_mul_f32_e32 v72, 0x3f317217, v132
	v_mul_f32_e32 v73, 0x3f317217, v121
	v_mul_f32_e32 v74, 0x3f317217, v125
	v_mul_f32_e32 v75, 0x3f317217, v129
	v_mul_f32_e32 v76, 0x3f317217, v133
	v_mul_f32_e32 v77, 0x3f317217, v122
	v_mul_f32_e32 v78, 0x3f317217, v126
	v_mul_f32_e32 v79, 0x3f317217, v130
	v_mul_f32_e32 v80, 0x3f317217, v134
	v_mul_f32_e32 v81, 0x3f317217, v123
	v_mul_f32_e32 v82, 0x3f317217, v127
	v_mul_f32_e32 v83, 0x3f317217, v131
	v_mul_f32_e32 v84, 0x3f317217, v135
	v_fma_f32 v69, v120, s15, -v69
	v_fma_f32 v70, v124, s15, -v70
	v_fma_f32 v71, v128, s15, -v71
	v_fma_f32 v72, v132, s15, -v72
	v_fma_f32 v73, v121, s15, -v73
	v_fma_f32 v74, v125, s15, -v74
	v_fma_f32 v75, v129, s15, -v75
	v_fma_f32 v76, v133, s15, -v76
	v_fma_f32 v77, v122, s15, -v77
	v_fma_f32 v78, v126, s15, -v78
	v_fma_f32 v79, v130, s15, -v79
	v_fma_f32 v80, v134, s15, -v80
	v_fma_f32 v81, v123, s15, -v81
	v_fma_f32 v82, v127, s15, -v82
	v_fma_f32 v83, v131, s15, -v83
	v_fma_f32 v84, v135, s15, -v84
	v_fmac_f32_e32 v69, 0x3377d1cf, v120
	v_fmac_f32_e32 v70, 0x3377d1cf, v124
	v_fmac_f32_e32 v71, 0x3377d1cf, v128
	v_fmac_f32_e32 v72, 0x3377d1cf, v132
	v_fmac_f32_e32 v73, 0x3377d1cf, v121
	v_fmac_f32_e32 v74, 0x3377d1cf, v125
	v_fmac_f32_e32 v75, 0x3377d1cf, v129
	v_fmac_f32_e32 v76, 0x3377d1cf, v133
	v_fmac_f32_e32 v77, 0x3377d1cf, v122
	v_fmac_f32_e32 v78, 0x3377d1cf, v126
	v_fmac_f32_e32 v79, 0x3377d1cf, v130
	v_fmac_f32_e32 v80, 0x3377d1cf, v134
	v_fmac_f32_e32 v81, 0x3377d1cf, v123
	v_fmac_f32_e32 v82, 0x3377d1cf, v127
	v_fmac_f32_e32 v83, 0x3377d1cf, v131
	v_fmac_f32_e32 v84, 0x3377d1cf, v135
	v_fmac_f32_e32 v69, 0x3f317217, v120
	v_fmac_f32_e32 v70, 0x3f317217, v124
	v_fmac_f32_e32 v71, 0x3f317217, v128
	v_fmac_f32_e32 v72, 0x3f317217, v132
	v_fmac_f32_e32 v73, 0x3f317217, v121
	v_fmac_f32_e32 v74, 0x3f317217, v125
	v_fmac_f32_e32 v75, 0x3f317217, v129
	v_fmac_f32_e32 v76, 0x3f317217, v133
	v_fmac_f32_e32 v77, 0x3f317217, v122
	v_fmac_f32_e32 v78, 0x3f317217, v126
	v_fmac_f32_e32 v79, 0x3f317217, v130
	v_fmac_f32_e32 v80, 0x3f317217, v134
	v_fmac_f32_e32 v81, 0x3f317217, v123
	v_fmac_f32_e32 v82, 0x3f317217, v127
	v_fmac_f32_e32 v83, 0x3f317217, v131
	v_fmac_f32_e32 v84, 0x3f317217, v135
	v_sub_f32_e32 v120, v53, v69
	v_sub_f32_e32 v124, v54, v70
	v_sub_f32_e32 v128, v55, v71
	v_sub_f32_e32 v132, v56, v72
	v_sub_f32_e32 v121, v57, v73
	v_sub_f32_e32 v125, v58, v74
	v_sub_f32_e32 v129, v59, v75
	v_sub_f32_e32 v133, v60, v76
	v_sub_f32_e32 v122, v61, v77
	v_sub_f32_e32 v126, v62, v78
	v_sub_f32_e32 v130, v63, v79
	v_sub_f32_e32 v134, v64, v80
	v_sub_f32_e32 v123, v65, v81
	v_sub_f32_e32 v127, v66, v82
	v_sub_f32_e32 v131, v67, v83
	v_sub_f32_e32 v135, v68, v84
	v_fma_mixlo_f16 v86, v120, s17, 0
	v_fma_mixlo_f16 v87, v128, s17, 0
	v_fma_mixlo_f16 v88, v121, s17, 0
	v_fma_mixlo_f16 v89, v129, s17, 0
	v_fma_mixlo_f16 v90, v122, s17, 0
	v_fma_mixlo_f16 v91, v130, s17, 0
	v_fma_mixlo_f16 v92, v123, s17, 0
	v_fma_mixlo_f16 v93, v131, s17, 0
	v_fma_mixhi_f16 v86, v124, s17, 0
	v_fma_mixhi_f16 v87, v132, s17, 0
	v_fma_mixhi_f16 v88, v125, s17, 0
	v_fma_mixhi_f16 v89, v133, s17, 0
	v_fma_mixhi_f16 v90, v126, s17, 0
	v_fma_mixhi_f16 v91, v134, s17, 0
	v_fma_mixhi_f16 v92, v127, s17, 0
	v_fma_mixhi_f16 v93, v135, s17, 0
	global_store_dwordx2 v[168:169], v[86:87], off
	global_store_dwordx2 v[168:169], v[88:89], off offset:1024
	global_store_dwordx2 v[168:169], v[90:91], off offset:2048
	global_store_dwordx2 v[168:169], v[92:93], off offset:3072
	v_add_f32_e32 v136, v116, v136
	v_add_f32_e32 v140, v117, v140
	v_add_f32_e32 v144, v118, v144
	v_add_f32_e32 v148, v119, v148
	v_add_f32_e32 v137, v116, v137
	v_add_f32_e32 v141, v117, v141
	v_add_f32_e32 v145, v118, v145
	v_add_f32_e32 v149, v119, v149
	v_add_f32_e32 v138, v116, v138
	v_add_f32_e32 v142, v117, v142
	v_add_f32_e32 v146, v118, v146
	v_add_f32_e32 v150, v119, v150
	v_add_f32_e32 v139, v116, v139
	v_add_f32_e32 v143, v117, v143
	v_add_f32_e32 v147, v118, v147
	v_add_f32_e32 v151, v119, v151
	v_min_f32_e32 v53, 0, v136
	v_min_f32_e32 v54, 0, v140
	v_min_f32_e32 v55, 0, v144
	v_min_f32_e32 v56, 0, v148
	v_min_f32_e32 v57, 0, v137
	v_min_f32_e32 v58, 0, v141
	v_min_f32_e32 v59, 0, v145
	v_min_f32_e32 v60, 0, v149
	v_min_f32_e32 v61, 0, v138
	v_min_f32_e32 v62, 0, v142
	v_min_f32_e32 v63, 0, v146
	v_min_f32_e32 v64, 0, v150
	v_min_f32_e32 v65, 0, v139
	v_min_f32_e32 v66, 0, v143
	v_min_f32_e32 v67, 0, v147
	v_min_f32_e32 v68, 0, v151
	v_mul_f32_e64 v136, |v136|, s13
	v_mul_f32_e64 v140, |v140|, s13
	v_mul_f32_e64 v144, |v144|, s13
	v_mul_f32_e64 v148, |v148|, s13
	v_mul_f32_e64 v137, |v137|, s13
	v_mul_f32_e64 v141, |v141|, s13
	v_mul_f32_e64 v145, |v145|, s13
	v_mul_f32_e64 v149, |v149|, s13
	v_mul_f32_e64 v138, |v138|, s13
	v_mul_f32_e64 v142, |v142|, s13
	v_mul_f32_e64 v146, |v146|, s13
	v_mul_f32_e64 v150, |v150|, s13
	v_mul_f32_e64 v139, |v139|, s13
	v_mul_f32_e64 v143, |v143|, s13
	v_mul_f32_e64 v147, |v147|, s13
	v_mul_f32_e64 v151, |v151|, s13
	v_exp_f32_e32 v136, v136
	v_exp_f32_e32 v140, v140
	v_exp_f32_e32 v144, v144
	v_exp_f32_e32 v148, v148
	v_exp_f32_e32 v137, v137
	v_exp_f32_e32 v141, v141
	v_exp_f32_e32 v145, v145
	v_exp_f32_e32 v149, v149
	v_exp_f32_e32 v138, v138
	v_exp_f32_e32 v142, v142
	v_exp_f32_e32 v146, v146
	v_exp_f32_e32 v150, v150
	v_exp_f32_e32 v139, v139
	v_exp_f32_e32 v143, v143
	v_exp_f32_e32 v147, v147
	v_exp_f32_e32 v151, v151
	v_add_f32_e32 v136, 1.0, v136
	v_add_f32_e32 v140, 1.0, v140
	v_add_f32_e32 v144, 1.0, v144
	v_add_f32_e32 v148, 1.0, v148
	v_add_f32_e32 v137, 1.0, v137
	v_add_f32_e32 v141, 1.0, v141
	v_add_f32_e32 v145, 1.0, v145
	v_add_f32_e32 v149, 1.0, v149
	v_add_f32_e32 v138, 1.0, v138
	v_add_f32_e32 v142, 1.0, v142
	v_add_f32_e32 v146, 1.0, v146
	v_add_f32_e32 v150, 1.0, v150
	v_add_f32_e32 v139, 1.0, v139
	v_add_f32_e32 v143, 1.0, v143
	v_add_f32_e32 v147, 1.0, v147
	v_add_f32_e32 v151, 1.0, v151
	v_log_f32_e32 v136, v136
	v_log_f32_e32 v140, v140
	v_log_f32_e32 v144, v144
	v_log_f32_e32 v148, v148
	v_log_f32_e32 v137, v137
	v_log_f32_e32 v141, v141
	v_log_f32_e32 v145, v145
	v_log_f32_e32 v149, v149
	v_log_f32_e32 v138, v138
	v_log_f32_e32 v142, v142
	v_log_f32_e32 v146, v146
	v_log_f32_e32 v150, v150
	v_log_f32_e32 v139, v139
	v_log_f32_e32 v143, v143
	v_log_f32_e32 v147, v147
	v_log_f32_e32 v151, v151
	v_mul_f32_e32 v69, 0x3f317217, v136
	v_mul_f32_e32 v70, 0x3f317217, v140
	v_mul_f32_e32 v71, 0x3f317217, v144
	v_mul_f32_e32 v72, 0x3f317217, v148
	v_mul_f32_e32 v73, 0x3f317217, v137
	v_mul_f32_e32 v74, 0x3f317217, v141
	v_mul_f32_e32 v75, 0x3f317217, v145
	v_mul_f32_e32 v76, 0x3f317217, v149
	v_mul_f32_e32 v77, 0x3f317217, v138
	v_mul_f32_e32 v78, 0x3f317217, v142
	v_mul_f32_e32 v79, 0x3f317217, v146
	v_mul_f32_e32 v80, 0x3f317217, v150
	v_mul_f32_e32 v81, 0x3f317217, v139
	v_mul_f32_e32 v82, 0x3f317217, v143
	v_mul_f32_e32 v83, 0x3f317217, v147
	v_mul_f32_e32 v84, 0x3f317217, v151
	v_fma_f32 v69, v136, s15, -v69
	v_fma_f32 v70, v140, s15, -v70
	v_fma_f32 v71, v144, s15, -v71
	v_fma_f32 v72, v148, s15, -v72
	v_fma_f32 v73, v137, s15, -v73
	v_fma_f32 v74, v141, s15, -v74
	v_fma_f32 v75, v145, s15, -v75
	v_fma_f32 v76, v149, s15, -v76
	v_fma_f32 v77, v138, s15, -v77
	v_fma_f32 v78, v142, s15, -v78
	v_fma_f32 v79, v146, s15, -v79
	v_fma_f32 v80, v150, s15, -v80
	v_fma_f32 v81, v139, s15, -v81
	v_fma_f32 v82, v143, s15, -v82
	v_fma_f32 v83, v147, s15, -v83
	v_fma_f32 v84, v151, s15, -v84
	v_fmac_f32_e32 v69, 0x3377d1cf, v136
	v_fmac_f32_e32 v70, 0x3377d1cf, v140
	v_fmac_f32_e32 v71, 0x3377d1cf, v144
	v_fmac_f32_e32 v72, 0x3377d1cf, v148
	v_fmac_f32_e32 v73, 0x3377d1cf, v137
	v_fmac_f32_e32 v74, 0x3377d1cf, v141
	v_fmac_f32_e32 v75, 0x3377d1cf, v145
	v_fmac_f32_e32 v76, 0x3377d1cf, v149
	v_fmac_f32_e32 v77, 0x3377d1cf, v138
	v_fmac_f32_e32 v78, 0x3377d1cf, v142
	v_fmac_f32_e32 v79, 0x3377d1cf, v146
	v_fmac_f32_e32 v80, 0x3377d1cf, v150
	v_fmac_f32_e32 v81, 0x3377d1cf, v139
	v_fmac_f32_e32 v82, 0x3377d1cf, v143
	v_fmac_f32_e32 v83, 0x3377d1cf, v147
	v_fmac_f32_e32 v84, 0x3377d1cf, v151
	v_fmac_f32_e32 v69, 0x3f317217, v136
	v_fmac_f32_e32 v70, 0x3f317217, v140
	v_fmac_f32_e32 v71, 0x3f317217, v144
	v_fmac_f32_e32 v72, 0x3f317217, v148
	v_fmac_f32_e32 v73, 0x3f317217, v137
	v_fmac_f32_e32 v74, 0x3f317217, v141
	v_fmac_f32_e32 v75, 0x3f317217, v145
	v_fmac_f32_e32 v76, 0x3f317217, v149
	v_fmac_f32_e32 v77, 0x3f317217, v138
	v_fmac_f32_e32 v78, 0x3f317217, v142
	v_fmac_f32_e32 v79, 0x3f317217, v146
	v_fmac_f32_e32 v80, 0x3f317217, v150
	v_fmac_f32_e32 v81, 0x3f317217, v139
	v_fmac_f32_e32 v82, 0x3f317217, v143
	v_fmac_f32_e32 v83, 0x3f317217, v147
	v_fmac_f32_e32 v84, 0x3f317217, v151
	v_sub_f32_e32 v136, v53, v69
	v_sub_f32_e32 v140, v54, v70
	v_sub_f32_e32 v144, v55, v71
	v_sub_f32_e32 v148, v56, v72
	v_sub_f32_e32 v137, v57, v73
	v_sub_f32_e32 v141, v58, v74
	v_sub_f32_e32 v145, v59, v75
	v_sub_f32_e32 v149, v60, v76
	v_sub_f32_e32 v138, v61, v77
	v_sub_f32_e32 v142, v62, v78
	v_sub_f32_e32 v146, v63, v79
	v_sub_f32_e32 v150, v64, v80
	v_sub_f32_e32 v139, v65, v81
	v_sub_f32_e32 v143, v66, v82
	v_sub_f32_e32 v147, v67, v83
	v_sub_f32_e32 v151, v68, v84
	v_fma_mixlo_f16 v86, v136, s17, 0
	v_fma_mixlo_f16 v87, v144, s17, 0
	v_fma_mixlo_f16 v88, v137, s17, 0
	v_fma_mixlo_f16 v89, v145, s17, 0
	v_fma_mixlo_f16 v90, v138, s17, 0
	v_fma_mixlo_f16 v91, v146, s17, 0
	v_fma_mixlo_f16 v92, v139, s17, 0
	v_fma_mixlo_f16 v93, v147, s17, 0
	v_fma_mixhi_f16 v86, v140, s17, 0
	v_fma_mixhi_f16 v87, v148, s17, 0
	v_fma_mixhi_f16 v88, v141, s17, 0
	v_fma_mixhi_f16 v89, v149, s17, 0
	v_fma_mixhi_f16 v90, v142, s17, 0
	v_fma_mixhi_f16 v91, v150, s17, 0
	v_fma_mixhi_f16 v92, v143, s17, 0
	v_fma_mixhi_f16 v93, v151, s17, 0
	global_store_dwordx2 v[170:171], v[86:87], off
	global_store_dwordx2 v[170:171], v[88:89], off offset:1024
	global_store_dwordx2 v[170:171], v[90:91], off offset:2048
	global_store_dwordx2 v[170:171], v[92:93], off offset:3072
	v_add_f32_e32 v152, v116, v152
	v_add_f32_e32 v156, v117, v156
	v_add_f32_e32 v160, v118, v160
	v_add_f32_e32 v164, v119, v164
	v_add_f32_e32 v153, v116, v153
	v_add_f32_e32 v157, v117, v157
	v_add_f32_e32 v161, v118, v161
	v_add_f32_e32 v165, v119, v165
	v_add_f32_e32 v154, v116, v154
	v_add_f32_e32 v158, v117, v158
	v_add_f32_e32 v162, v118, v162
	v_add_f32_e32 v166, v119, v166
	v_add_f32_e32 v155, v116, v155
	v_add_f32_e32 v159, v117, v159
	v_add_f32_e32 v163, v118, v163
	v_add_f32_e32 v167, v119, v167
	v_min_f32_e32 v53, 0, v152
	v_min_f32_e32 v54, 0, v156
	v_min_f32_e32 v55, 0, v160
	v_min_f32_e32 v56, 0, v164
	v_min_f32_e32 v57, 0, v153
	v_min_f32_e32 v58, 0, v157
	v_min_f32_e32 v59, 0, v161
	v_min_f32_e32 v60, 0, v165
	v_min_f32_e32 v61, 0, v154
	v_min_f32_e32 v62, 0, v158
	v_min_f32_e32 v63, 0, v162
	v_min_f32_e32 v64, 0, v166
	v_min_f32_e32 v65, 0, v155
	v_min_f32_e32 v66, 0, v159
	v_min_f32_e32 v67, 0, v163
	v_min_f32_e32 v68, 0, v167
	v_mul_f32_e64 v152, |v152|, s13
	v_mul_f32_e64 v156, |v156|, s13
	v_mul_f32_e64 v160, |v160|, s13
	v_mul_f32_e64 v164, |v164|, s13
	v_mul_f32_e64 v153, |v153|, s13
	v_mul_f32_e64 v157, |v157|, s13
	v_mul_f32_e64 v161, |v161|, s13
	v_mul_f32_e64 v165, |v165|, s13
	v_mul_f32_e64 v154, |v154|, s13
	v_mul_f32_e64 v158, |v158|, s13
	v_mul_f32_e64 v162, |v162|, s13
	v_mul_f32_e64 v166, |v166|, s13
	v_mul_f32_e64 v155, |v155|, s13
	v_mul_f32_e64 v159, |v159|, s13
	v_mul_f32_e64 v163, |v163|, s13
	v_mul_f32_e64 v167, |v167|, s13
	v_exp_f32_e32 v152, v152
	v_exp_f32_e32 v156, v156
	v_exp_f32_e32 v160, v160
	v_exp_f32_e32 v164, v164
	v_exp_f32_e32 v153, v153
	v_exp_f32_e32 v157, v157
	v_exp_f32_e32 v161, v161
	v_exp_f32_e32 v165, v165
	v_exp_f32_e32 v154, v154
	v_exp_f32_e32 v158, v158
	v_exp_f32_e32 v162, v162
	v_exp_f32_e32 v166, v166
	v_exp_f32_e32 v155, v155
	v_exp_f32_e32 v159, v159
	v_exp_f32_e32 v163, v163
	v_exp_f32_e32 v167, v167
	v_add_f32_e32 v152, 1.0, v152
	v_add_f32_e32 v156, 1.0, v156
	v_add_f32_e32 v160, 1.0, v160
	v_add_f32_e32 v164, 1.0, v164
	v_add_f32_e32 v153, 1.0, v153
	v_add_f32_e32 v157, 1.0, v157
	v_add_f32_e32 v161, 1.0, v161
	v_add_f32_e32 v165, 1.0, v165
	v_add_f32_e32 v154, 1.0, v154
	v_add_f32_e32 v158, 1.0, v158
	v_add_f32_e32 v162, 1.0, v162
	v_add_f32_e32 v166, 1.0, v166
	v_add_f32_e32 v155, 1.0, v155
	v_add_f32_e32 v159, 1.0, v159
	v_add_f32_e32 v163, 1.0, v163
	v_add_f32_e32 v167, 1.0, v167
	v_log_f32_e32 v152, v152
	v_log_f32_e32 v156, v156
	v_log_f32_e32 v160, v160
	v_log_f32_e32 v164, v164
	v_log_f32_e32 v153, v153
	v_log_f32_e32 v157, v157
	v_log_f32_e32 v161, v161
	v_log_f32_e32 v165, v165
	v_log_f32_e32 v154, v154
	v_log_f32_e32 v158, v158
	v_log_f32_e32 v162, v162
	v_log_f32_e32 v166, v166
	v_log_f32_e32 v155, v155
	v_log_f32_e32 v159, v159
	v_log_f32_e32 v163, v163
	v_log_f32_e32 v167, v167
	v_mul_f32_e32 v69, 0x3f317217, v152
	v_mul_f32_e32 v70, 0x3f317217, v156
	v_mul_f32_e32 v71, 0x3f317217, v160
	v_mul_f32_e32 v72, 0x3f317217, v164
	v_mul_f32_e32 v73, 0x3f317217, v153
	v_mul_f32_e32 v74, 0x3f317217, v157
	v_mul_f32_e32 v75, 0x3f317217, v161
	v_mul_f32_e32 v76, 0x3f317217, v165
	v_mul_f32_e32 v77, 0x3f317217, v154
	v_mul_f32_e32 v78, 0x3f317217, v158
	v_mul_f32_e32 v79, 0x3f317217, v162
	v_mul_f32_e32 v80, 0x3f317217, v166
	v_mul_f32_e32 v81, 0x3f317217, v155
	v_mul_f32_e32 v82, 0x3f317217, v159
	v_mul_f32_e32 v83, 0x3f317217, v163
	v_mul_f32_e32 v84, 0x3f317217, v167
	v_fma_f32 v69, v152, s15, -v69
	v_fma_f32 v70, v156, s15, -v70
	v_fma_f32 v71, v160, s15, -v71
	v_fma_f32 v72, v164, s15, -v72
	v_fma_f32 v73, v153, s15, -v73
	v_fma_f32 v74, v157, s15, -v74
	v_fma_f32 v75, v161, s15, -v75
	v_fma_f32 v76, v165, s15, -v76
	v_fma_f32 v77, v154, s15, -v77
	v_fma_f32 v78, v158, s15, -v78
	v_fma_f32 v79, v162, s15, -v79
	v_fma_f32 v80, v166, s15, -v80
	v_fma_f32 v81, v155, s15, -v81
	v_fma_f32 v82, v159, s15, -v82
	v_fma_f32 v83, v163, s15, -v83
	v_fma_f32 v84, v167, s15, -v84
	v_fmac_f32_e32 v69, 0x3377d1cf, v152
	v_fmac_f32_e32 v70, 0x3377d1cf, v156
	v_fmac_f32_e32 v71, 0x3377d1cf, v160
	v_fmac_f32_e32 v72, 0x3377d1cf, v164
	v_fmac_f32_e32 v73, 0x3377d1cf, v153
	v_fmac_f32_e32 v74, 0x3377d1cf, v157
	v_fmac_f32_e32 v75, 0x3377d1cf, v161
	v_fmac_f32_e32 v76, 0x3377d1cf, v165
	v_fmac_f32_e32 v77, 0x3377d1cf, v154
	v_fmac_f32_e32 v78, 0x3377d1cf, v158
	v_fmac_f32_e32 v79, 0x3377d1cf, v162
	v_fmac_f32_e32 v80, 0x3377d1cf, v166
	v_fmac_f32_e32 v81, 0x3377d1cf, v155
	v_fmac_f32_e32 v82, 0x3377d1cf, v159
	v_fmac_f32_e32 v83, 0x3377d1cf, v163
	v_fmac_f32_e32 v84, 0x3377d1cf, v167
	v_fmac_f32_e32 v69, 0x3f317217, v152
	v_fmac_f32_e32 v70, 0x3f317217, v156
	v_fmac_f32_e32 v71, 0x3f317217, v160
	v_fmac_f32_e32 v72, 0x3f317217, v164
	v_fmac_f32_e32 v73, 0x3f317217, v153
	v_fmac_f32_e32 v74, 0x3f317217, v157
	v_fmac_f32_e32 v75, 0x3f317217, v161
	v_fmac_f32_e32 v76, 0x3f317217, v165
	v_fmac_f32_e32 v77, 0x3f317217, v154
	v_fmac_f32_e32 v78, 0x3f317217, v158
	v_fmac_f32_e32 v79, 0x3f317217, v162
	v_fmac_f32_e32 v80, 0x3f317217, v166
	v_fmac_f32_e32 v81, 0x3f317217, v155
	v_fmac_f32_e32 v82, 0x3f317217, v159
	v_fmac_f32_e32 v83, 0x3f317217, v163
	v_fmac_f32_e32 v84, 0x3f317217, v167
	v_sub_f32_e32 v152, v53, v69
	v_sub_f32_e32 v156, v54, v70
	v_sub_f32_e32 v160, v55, v71
	v_sub_f32_e32 v164, v56, v72
	v_sub_f32_e32 v153, v57, v73
	v_sub_f32_e32 v157, v58, v74
	v_sub_f32_e32 v161, v59, v75
	v_sub_f32_e32 v165, v60, v76
	v_sub_f32_e32 v154, v61, v77
	v_sub_f32_e32 v158, v62, v78
	v_sub_f32_e32 v162, v63, v79
	v_sub_f32_e32 v166, v64, v80
	v_sub_f32_e32 v155, v65, v81
	v_sub_f32_e32 v159, v66, v82
	v_sub_f32_e32 v163, v67, v83
	v_sub_f32_e32 v167, v68, v84
	v_fma_mixlo_f16 v86, v152, s17, 0
	v_fma_mixlo_f16 v87, v160, s17, 0
	v_fma_mixlo_f16 v88, v153, s17, 0
	v_fma_mixlo_f16 v89, v161, s17, 0
	v_fma_mixlo_f16 v90, v154, s17, 0
	v_fma_mixlo_f16 v91, v162, s17, 0
	v_fma_mixlo_f16 v92, v155, s17, 0
	v_fma_mixlo_f16 v93, v163, s17, 0
	v_fma_mixhi_f16 v86, v156, s17, 0
	v_fma_mixhi_f16 v87, v164, s17, 0
	v_fma_mixhi_f16 v88, v157, s17, 0
	v_fma_mixhi_f16 v89, v165, s17, 0
	v_fma_mixhi_f16 v90, v158, s17, 0
	v_fma_mixhi_f16 v91, v166, s17, 0
	v_fma_mixhi_f16 v92, v159, s17, 0
	v_fma_mixhi_f16 v93, v167, s17, 0
	global_store_dwordx2 v[172:173], v[86:87], off
	global_store_dwordx2 v[172:173], v[88:89], off offset:1024
	global_store_dwordx2 v[172:173], v[90:91], off offset:2048
	global_store_dwordx2 v[172:173], v[92:93], off offset:3072
	s_add_i32 s19, s19, s26
	s_add_i32 s10, s10, s34
	s_cmpk_gt_i32 s19, 0xff
	s_barrier
	s_cbranch_scc0 .LBB0_225
